# scan phases: branch-free row position selection for the next-chunk loads (one SALU select per step, v_cndmask per load pair)
# speedup vs baseline: 1.0001x; 1.0001x over previous
.LBB0_459:
	s_or_b64 exec, exec, s[34:35]
	v_cvt_pk_bf16_f32 v36, v12, v13
	v_cvt_pk_bf16_f32 v37, v14, v15
	v_cvt_pk_bf16_f32 v44, v32, v33
	v_cvt_pk_bf16_f32 v45, v34, v35
	v_cvt_pk_bf16_f32 v38, v16, v17
	v_cvt_pk_bf16_f32 v39, v18, v19
	ds_write2_b64 v200, v[36:37], v[44:45] offset1:4
	v_cvt_pk_bf16_f32 v36, v28, v29
	v_cvt_pk_bf16_f32 v37, v30, v31
	v_add_u32_e32 v209, 0x2000, v200
	v_cvt_pk_bf16_f32 v40, v8, v9
	v_cvt_pk_bf16_f32 v41, v10, v11
	ds_write2_b64 v209, v[38:39], v[36:37] offset0:32 offset1:36
	v_cvt_pk_bf16_f32 v36, v24, v25
	v_cvt_pk_bf16_f32 v37, v26, v27
	v_add_u32_e32 v210, 0x4000, v200
	v_cvt_pk_bf16_f32 v42, v4, v5
	v_cvt_pk_bf16_f32 v43, v6, v7
	ds_write2_b64 v210, v[40:41], v[36:37] offset0:64 offset1:68
	v_cvt_pk_bf16_f32 v36, v20, v21
	v_cvt_pk_bf16_f32 v37, v22, v23
	v_add_u32_e32 v211, 0x6000, v200
	s_add_i32 s55, s56, 1
	ds_write2_b64 v211, v[42:43], v[36:37] offset0:96 offset1:100
	s_cmp_gt_u32 s56, 2
	v_cndmask_b32_e64 v36, 0, 1, s[64:65]
	s_cselect_b64 s[72:73], -1, 0
	v_cmp_ne_u32_e64 s[34:35], 1, v36
	s_andn2_b64 vcc, exec, s[64:65]
	s_lshl_b32 s57, s55, 6
	s_waitcnt lgkmcnt(0)
	s_barrier
	s_movk_i32 s98, 0xff
	s_cmp_lg_u64 s[72:73], 0
	s_cmovk_i32 s98, 0x21ff
	v_add_u32_e32 v37, s57, v145
	v_sub_u32_e32 v36, s98, v37
	v_add_u32_e32 v37, s54, v192
	v_cndmask_b32_e64 v36, v37, v36, s[64:65]
.LBB0_465:
	v_ashrrev_i32_e32 v37, 31, v36
	v_lshl_add_u64 v[36:37], s[66:67], 0, v[36:37]
	v_lshlrev_b64 v[36:37], 12, v[36:37]
	v_lshl_add_u64 v[38:39], v[160:161], 0, v[36:37]
	v_lshl_add_u64 v[36:37], v[162:163], 0, v[36:37]
	global_load_dwordx4 v[64:67], v[38:39], off
	global_load_dwordx4 v[60:63], v[36:37], off
	v_cndmask_b32_e64 v36, 0, 1, s[72:73]
	s_and_b64 vcc, exec, s[34:35]
	v_cmp_ne_u32_e64 s[36:37], 1, v36
	v_add_u32_e32 v37, s57, v168
	v_sub_u32_e32 v36, s98, v37
	v_add_u32_e32 v37, s54, v191
	v_cndmask_b32_e64 v36, v37, v36, s[64:65]
.LBB0_471:
	v_ashrrev_i32_e32 v37, 31, v36
	v_lshl_add_u64 v[36:37], s[66:67], 0, v[36:37]
	v_lshlrev_b64 v[36:37], 12, v[36:37]
	v_lshl_add_u64 v[38:39], v[160:161], 0, v[36:37]
	v_lshl_add_u64 v[36:37], v[162:163], 0, v[36:37]
	global_load_dwordx4 v[56:59], v[38:39], off
	global_load_dwordx4 v[52:55], v[36:37], off
	s_and_b64 vcc, exec, s[34:35]
	v_add_u32_e32 v37, s57, v170
	v_sub_u32_e32 v36, s98, v37
	v_add_u32_e32 v37, s54, v190
	v_cndmask_b32_e64 v36, v37, v36, s[64:65]
.LBB0_477:
	v_ashrrev_i32_e32 v37, 31, v36
	v_lshl_add_u64 v[36:37], s[66:67], 0, v[36:37]
	v_lshlrev_b64 v[36:37], 12, v[36:37]
	v_lshl_add_u64 v[38:39], v[160:161], 0, v[36:37]
	v_lshl_add_u64 v[36:37], v[162:163], 0, v[36:37]
	global_load_dwordx4 v[48:51], v[38:39], off
	global_load_dwordx4 v[44:47], v[36:37], off
	s_and_b64 vcc, exec, s[34:35]
	v_add_u32_e32 v37, s57, v172
	v_sub_u32_e32 v36, s98, v37
	v_add_u32_e32 v37, s54, v189
	v_cndmask_b32_e64 v36, v37, v36, s[64:65]
.LBB0_483:
	v_ashrrev_i32_e32 v37, 31, v36
	v_lshl_add_u64 v[36:37], s[66:67], 0, v[36:37]
	v_lshlrev_b64 v[36:37], 12, v[36:37]
	v_lshl_add_u64 v[38:39], v[160:161], 0, v[36:37]
	v_lshl_add_u64 v[36:37], v[162:163], 0, v[36:37]
	global_load_dwordx4 v[40:43], v[38:39], off
	s_nop 0
	global_load_dwordx4 v[36:39], v[36:37], off
	s_and_saveexec_b64 s[36:37], s[4:5]
	s_cbranch_execz .LBB0_491
	s_and_b64 vcc, exec, s[34:35]
	v_or_b32_e32 v1, s57, v129
	v_sub_u32_e32 v0, s98, v1
	v_add_u32_e32 v1, s54, v188
	v_cndmask_b32_e64 v0, v1, v0, s[64:65]

.LBB0_3326:
	s_or_b64 exec, exec, s[4:5]
	v_cvt_pk_bf16_f32 v12, v4, v5
	v_cvt_pk_bf16_f32 v13, v6, v7
	ds_write_b64 v127, v[12:13] offset:53248
	v_cvt_pk_bf16_f32 v12, v8, v9
	v_cvt_pk_bf16_f32 v13, v10, v11
	s_add_i32 s76, s67, 1
	ds_write_b64 v127, v[12:13] offset:57600
	s_cmp_gt_u32 s67, 2
	v_cndmask_b32_e64 v12, 0, 1, s[64:65]
	s_cselect_b64 s[74:75], -1, 0
	s_lshl_b32 s68, s76, 6
	v_cmp_ne_u32_e64 s[48:49], 1, v12
	s_andn2_b64 vcc, exec, s[64:65]
	v_add_u32_e32 v14, s66, v90
	s_waitcnt lgkmcnt(0)
	s_barrier
	s_movk_i32 s98, 0xff
	s_cmp_lg_u64 s[74:75], 0
	s_cmovk_i32 s98, 0x21ff
	v_add_u32_e32 v13, s68, v90
	v_sub_u32_e32 v12, s98, v13
	v_add_u32_e32 v13, 64, v14
	v_cndmask_b32_e64 v12, v13, v12, s[64:65]
.LBB0_3332:
	v_ashrrev_i32_e32 v13, 31, v12
	v_lshl_add_u64 v[12:13], v[12:13], 0, s[0:1]
	v_mad_u64_u32 v[16:17], s[4:5], v12, s60, v[56:57]
	v_mad_i32_i24 v17, v13, s60, v17
	global_load_dword v51, v[16:17], off
	v_mad_u64_u32 v[16:17], s[4:5], v12, s60, v[58:59]
	v_mad_i32_i24 v17, v13, s60, v17
	global_load_dword v64, v[16:17], off
	v_cndmask_b32_e64 v12, 0, 1, s[74:75]
	s_and_b64 vcc, exec, s[48:49]
	v_cmp_ne_u32_e64 s[50:51], 1, v12
	v_add_u32_e32 v13, s68, v92
	v_sub_u32_e32 v12, s98, v13
	v_add_u32_e32 v13, 0x41, v14
	v_cndmask_b32_e64 v12, v13, v12, s[64:65]
.LBB0_3338:
	v_ashrrev_i32_e32 v13, 31, v12
	v_lshl_add_u64 v[12:13], v[12:13], 0, s[0:1]
	v_mad_u64_u32 v[16:17], s[4:5], v12, s60, v[56:57]
	v_mad_i32_i24 v17, v13, s60, v17
	global_load_dword v66, v[16:17], off
	v_mad_u64_u32 v[16:17], s[4:5], v12, s60, v[58:59]
	v_mad_i32_i24 v17, v13, s60, v17
	global_load_dword v65, v[16:17], off
	s_and_b64 vcc, exec, s[48:49]
	v_add_u32_e32 v13, s68, v94
	v_sub_u32_e32 v12, s98, v13
	v_add_u32_e32 v13, 0x42, v14
	v_cndmask_b32_e64 v12, v13, v12, s[64:65]
.LBB0_3344:
	v_ashrrev_i32_e32 v13, 31, v12
	v_lshl_add_u64 v[12:13], v[12:13], 0, s[0:1]
	v_mad_u64_u32 v[16:17], s[4:5], v12, s60, v[56:57]
	v_mad_i32_i24 v17, v13, s60, v17
	global_load_dword v68, v[16:17], off
	v_mad_u64_u32 v[16:17], s[4:5], v12, s60, v[58:59]
	v_mad_i32_i24 v17, v13, s60, v17
	global_load_dword v67, v[16:17], off
	s_and_b64 vcc, exec, s[48:49]
	v_add_u32_e32 v13, s68, v96
	v_sub_u32_e32 v12, s98, v13
	v_add_u32_e32 v13, 0x43, v14
	v_cndmask_b32_e64 v12, v13, v12, s[64:65]
.LBB0_3350:
	v_ashrrev_i32_e32 v13, 31, v12
	v_lshl_add_u64 v[12:13], v[12:13], 0, s[0:1]
	v_mad_u64_u32 v[16:17], s[4:5], v12, s60, v[56:57]
	v_mad_i32_i24 v17, v13, s60, v17
	global_load_dword v70, v[16:17], off
	v_mad_u64_u32 v[16:17], s[4:5], v12, s60, v[58:59]
	v_mad_i32_i24 v17, v13, s60, v17
	global_load_dword v69, v[16:17], off
	s_and_b64 vcc, exec, s[48:49]
	v_add_u32_e32 v13, s68, v98
	v_sub_u32_e32 v12, s98, v13
	v_add_u32_e32 v13, 0x44, v14
	v_cndmask_b32_e64 v12, v13, v12, s[64:65]
.LBB0_3356:
	v_ashrrev_i32_e32 v13, 31, v12
	v_lshl_add_u64 v[12:13], v[12:13], 0, s[0:1]
	v_mad_u64_u32 v[16:17], s[4:5], v12, s60, v[56:57]
	v_mad_i32_i24 v17, v13, s60, v17
	global_load_dword v72, v[16:17], off
	v_mad_u64_u32 v[16:17], s[4:5], v12, s60, v[58:59]
	v_mad_i32_i24 v17, v13, s60, v17
	global_load_dword v71, v[16:17], off
	s_and_b64 vcc, exec, s[48:49]
	v_add_u32_e32 v13, s68, v100
	v_sub_u32_e32 v12, s98, v13
	v_add_u32_e32 v13, 0x45, v14
	v_cndmask_b32_e64 v12, v13, v12, s[64:65]
.LBB0_3362:
	v_ashrrev_i32_e32 v13, 31, v12
	v_lshl_add_u64 v[12:13], v[12:13], 0, s[0:1]
	v_mad_u64_u32 v[16:17], s[4:5], v12, s60, v[56:57]
	v_mad_i32_i24 v17, v13, s60, v17
	global_load_dword v74, v[16:17], off
	v_mad_u64_u32 v[16:17], s[4:5], v12, s60, v[58:59]
	v_mad_i32_i24 v17, v13, s60, v17
	global_load_dword v73, v[16:17], off
	s_and_b64 vcc, exec, s[48:49]
	v_add_u32_e32 v13, s68, v102
	v_sub_u32_e32 v12, s98, v13
	v_add_u32_e32 v13, 0x46, v14
	v_cndmask_b32_e64 v12, v13, v12, s[64:65]
.LBB0_3368:
	v_ashrrev_i32_e32 v13, 31, v12
	v_lshl_add_u64 v[12:13], v[12:13], 0, s[0:1]
	v_mad_u64_u32 v[14:15], s[4:5], v12, s60, v[56:57]
	v_mad_i32_i24 v15, v13, s60, v15
	global_load_dword v77, v[14:15], off
	v_mad_u64_u32 v[14:15], s[4:5], v12, s60, v[58:59]
	v_mad_i32_i24 v15, v13, s60, v15
	global_load_dword v76, v[14:15], off
	s_and_b64 vcc, exec, s[48:49]
	v_add_u32_e32 v13, s68, v104
	v_sub_u32_e32 v12, s98, v13
	v_add_u32_e32 v13, s66, v123
	v_cndmask_b32_e64 v12, v13, v12, s[64:65]
.LBB0_3374:
	v_ashrrev_i32_e32 v13, 31, v12
	v_lshl_add_u64 v[12:13], v[12:13], 0, s[0:1]
	v_mad_u64_u32 v[14:15], s[4:5], v12, s60, v[56:57]
	v_mad_i32_i24 v15, v13, s60, v15
	global_load_dword v79, v[14:15], off
	v_mad_u64_u32 v[14:15], s[4:5], v12, s60, v[58:59]
	v_mad_i32_i24 v15, v13, s60, v15
	global_load_dword v78, v[14:15], off
	s_and_saveexec_b64 s[50:51], s[6:7]
	s_cbranch_execz .LBB0_3382
	s_and_b64 vcc, exec, s[48:49]
	v_or_b32_e32 v1, s68, v37
	v_sub_u32_e32 v0, s98, v1
	v_add_u32_e32 v1, s66, v122
	v_cndmask_b32_e64 v0, v1, v0, s[64:65]
